# norm-gain loads of the weight conversion (Wqkv0, W11) issued together per item instead of 4 serial round trips; on top of barrier deferral and EpiResid epilogues
# speedup vs baseline: 1.0052x; 1.0052x over previous
; #define LAS __attribute__((address_space(3)))
; #define LDS_WAIT() asm volatile("s_waitcnt lgkmcnt(0)" ::: "memory")
; __device__ __forceinline__ void tr_stage(const float* gain, int nblk, int item, int lane, const f32x4 (&wv)[8], LAS float* scr) {
;     const int k0 = 64 * (item / nblk);
; #pragma unroll
;     for (int i = 0; i < 8; ++i) { const int kk = 8 * i + (lane >> 3); const float gk = gain ? gain[k0 + kk] : 1.0f; LAS float* d = scr + kk * 33 + 4 * (lane & 7);
;         d[0] = wv[i][0] * gk; d[1] = wv[i][1] * gk; d[2] = wv[i][2] * gk; d[3] = wv[i][3] * gk; }
;     LDS_WAIT(); asm volatile("" ::: "memory");
.LBB0_34:
	s_mul_hi_i32 s4, s34, 0x2aaaaaab
	s_lshr_b32 s5, s4, 31
	s_ashr_i32 s35, s4, 5
	s_add_i32 s35, s35, s5
	v_cndmask_b32_e64 v40, 0, 1, s[14:15]
	v_cmp_ne_u32_e64 s[4:5], 1, v40
	s_andn2_b64 vcc, exec, s[14:15]
	s_lshl_b32 s10, s35, 6
	v_add_u32_e32 v110, s10, v34
	v_lshlrev_b32_e32 v110, 2, v110
	global_load_dword v112, v110, s[8:9]
	global_load_dword v113, v110, s[8:9] offset:32
	global_load_dword v114, v110, s[8:9] offset:64
	global_load_dword v115, v110, s[8:9] offset:96
	global_load_dword v116, v110, s[8:9] offset:128
	global_load_dword v117, v110, s[8:9] offset:160
	global_load_dword v118, v110, s[8:9] offset:192
	global_load_dword v119, v110, s[8:9] offset:224
	s_cbranch_vccnz .LBB0_48
	v_or_b32_e32 v46, s10, v34
	v_ashrrev_i32_e32 v47, 31, v46
	s_ashr_i32 s11, s10, 31
	v_lshl_add_u64 v[46:47], v[46:47], 2, s[8:9]
	v_lshl_add_u64 v[48:49], s[10:11], 0, v[34:35]
	s_waitcnt vmcnt(0)
	v_mov_b32_e32 v46, v112
	v_lshl_add_u64 v[48:49], v[48:49], 2, s[8:9]
	v_mov_b32_e32 v40, v113
	s_waitcnt vmcnt(1)
	v_pk_mul_f32 v[48:49], v[2:3], v[46:47] op_sel_hi:[1,0]
	v_pk_mul_f32 v[46:47], v[4:5], v[46:47] op_sel_hi:[1,0]
	ds_write2_b32 v42, v48, v49 offset1:1
	ds_write2_b32 v42, v46, v47 offset0:2 offset1:3
	s_cbranch_execnz .LBB0_37

; #define LAS __attribute__((address_space(3)))
; __device__ __forceinline__ void tr_stage(const float* gain, int nblk, int item, int lane, const f32x4 (&wv)[8], LAS float* scr) {
;     ...
; #pragma unroll
;     for (int i = 0; i < 8; ++i) { const int kk = 8 * i + (lane >> 3); const float gk = gain ? gain[k0 + kk] : 1.0f; LAS float* d = scr + kk * 33 + 4 * (lane & 7);
;         d[0] = wv[i][0] * gk; d[1] = wv[i][1] * gk; d[2] = wv[i][2] * gk; d[3] = wv[i][3] * gk; }
.LBB0_37:
	s_waitcnt vmcnt(0)
	v_pk_mul_f32 v[46:47], v[6:7], v[40:41] op_sel_hi:[1,0]
	v_add_u32_e32 v45, 0x420, v42
	ds_write2_b32 v45, v46, v47 offset1:1
	v_pk_mul_f32 v[46:47], v[8:9], v[40:41] op_sel_hi:[1,0]
	v_add_u32_e32 v40, 0x428, v42
	ds_write2_b32 v40, v46, v47 offset1:1
	s_and_b64 vcc, exec, s[4:5]
	v_add_u32_e32 v45, 0x840, v42
	v_add_u32_e32 v46, 0x848, v42
	s_cbranch_vccnz .LBB0_49
	s_ashr_i32 s11, s10, 31
	v_lshl_add_u64 v[48:49], s[10:11], 0, v[34:35]
	v_lshl_add_u64 v[48:49], v[48:49], 2, s[8:9]
	v_mov_b32_e32 v50, v114
	v_mov_b32_e32 v40, v115
	s_waitcnt vmcnt(1)
	v_pk_mul_f32 v[48:49], v[10:11], v[50:51] op_sel_hi:[1,0]
	v_pk_mul_f32 v[50:51], v[12:13], v[50:51] op_sel_hi:[1,0]
	ds_write2_b32 v45, v48, v49 offset1:1
	ds_write2_b32 v46, v50, v51 offset1:1
	s_cbranch_execnz .LBB0_40

; #define LAS __attribute__((address_space(3)))
; __device__ __forceinline__ void tr_stage(const float* gain, int nblk, int item, int lane, const f32x4 (&wv)[8], LAS float* scr) {
;     ...
; #pragma unroll
;     for (int i = 0; i < 8; ++i) { const int kk = 8 * i + (lane >> 3); const float gk = gain ? gain[k0 + kk] : 1.0f; LAS float* d = scr + kk * 33 + 4 * (lane & 7);
;         d[0] = wv[i][0] * gk; d[1] = wv[i][1] * gk; d[2] = wv[i][2] * gk; d[3] = wv[i][3] * gk; }
.LBB0_40:
	s_waitcnt vmcnt(0)
	v_pk_mul_f32 v[46:47], v[14:15], v[40:41] op_sel_hi:[1,0]
	v_add_u32_e32 v45, 0xc60, v42
	ds_write2_b32 v45, v46, v47 offset1:1
	v_pk_mul_f32 v[46:47], v[16:17], v[40:41] op_sel_hi:[1,0]
	v_add_u32_e32 v40, 0xc68, v42
	ds_write2_b32 v40, v46, v47 offset1:1
	s_and_b64 vcc, exec, s[4:5]
	v_add_u32_e32 v45, 0x1080, v42
	v_add_u32_e32 v46, 0x1088, v42
	s_cbranch_vccnz .LBB0_50
	s_ashr_i32 s11, s10, 31
	v_lshl_add_u64 v[48:49], s[10:11], 0, v[34:35]
	v_lshl_add_u64 v[48:49], v[48:49], 2, s[8:9]
	v_mov_b32_e32 v50, v116
	v_mov_b32_e32 v40, v117
	s_waitcnt vmcnt(1)
	v_pk_mul_f32 v[48:49], v[18:19], v[50:51] op_sel_hi:[1,0]
	v_pk_mul_f32 v[50:51], v[20:21], v[50:51] op_sel_hi:[1,0]
	ds_write2_b32 v45, v48, v49 offset1:1
	ds_write2_b32 v46, v50, v51 offset1:1
	s_cbranch_execnz .LBB0_43

; #define LAS __attribute__((address_space(3)))
; __device__ __forceinline__ void tr_stage(const float* gain, int nblk, int item, int lane, const f32x4 (&wv)[8], LAS float* scr) {
;     ...
; #pragma unroll
;     for (int i = 0; i < 8; ++i) { const int kk = 8 * i + (lane >> 3); const float gk = gain ? gain[k0 + kk] : 1.0f; LAS float* d = scr + kk * 33 + 4 * (lane & 7);
;         d[0] = wv[i][0] * gk; d[1] = wv[i][1] * gk; d[2] = wv[i][2] * gk; d[3] = wv[i][3] * gk; }
.LBB0_43:
	s_waitcnt vmcnt(0)
	v_pk_mul_f32 v[46:47], v[22:23], v[40:41] op_sel_hi:[1,0]
	v_add_u32_e32 v45, 0x14a0, v42
	ds_write2_b32 v45, v46, v47 offset1:1
	v_pk_mul_f32 v[46:47], v[24:25], v[40:41] op_sel_hi:[1,0]
	v_add_u32_e32 v40, 0x14a8, v42
	ds_write2_b32 v40, v46, v47 offset1:1
	s_and_b64 vcc, exec, s[4:5]
	v_add_u32_e32 v45, 0x18c0, v42
	v_add_u32_e32 v46, 0x18c8, v42
	s_cbranch_vccnz .LBB0_51
	s_ashr_i32 s11, s10, 31
	v_lshl_add_u64 v[48:49], s[10:11], 0, v[34:35]
	v_lshl_add_u64 v[48:49], v[48:49], 2, s[8:9]
	v_mov_b32_e32 v50, v118
	v_mov_b32_e32 v40, v119
	s_waitcnt vmcnt(1)
	v_pk_mul_f32 v[48:49], v[26:27], v[50:51] op_sel_hi:[1,0]
	v_pk_mul_f32 v[50:51], v[28:29], v[50:51] op_sel_hi:[1,0]
	ds_write2_b32 v45, v48, v49 offset1:1
	ds_write2_b32 v46, v50, v51 offset1:1
	s_cbranch_execnz .LBB0_46

; #define LAS __attribute__((address_space(3)))
; #define LDS_WAIT() asm volatile("s_waitcnt lgkmcnt(0)" ::: "memory")
; __device__ __forceinline__ void tr_stage(const float* gain, int nblk, int item, int lane, const f32x4 (&wv)[8], LAS float* scr) {
;     const int k0 = 64 * (item / nblk);
; #pragma unroll
;     for (int i = 0; i < 8; ++i) { const int kk = 8 * i + (lane >> 3); const float gk = gain ? gain[k0 + kk] : 1.0f; LAS float* d = scr + kk * 33 + 4 * (lane & 7);
;         d[0] = wv[i][0] * gk; d[1] = wv[i][1] * gk; d[2] = wv[i][2] * gk; d[3] = wv[i][3] * gk; }
;     LDS_WAIT(); asm volatile("" ::: "memory");
.LBB0_557:
	s_ashr_i32 s8, s53, 31
	s_lshr_b32 s8, s8, 24
	s_add_i32 s8, s53, s8
	s_ashr_i32 s54, s8, 8
	v_cndmask_b32_e64 v38, 0, 1, s[46:47]
	v_cmp_ne_u32_e64 s[8:9], 1, v38
	s_andn2_b64 vcc, exec, s[46:47]
	s_lshl_b32 s14, s54, 6
	v_add_u32_e32 v110, s14, v32
	v_lshlrev_b32_e32 v110, 2, v110
	global_load_dword v112, v110, s[12:13]
	global_load_dword v113, v110, s[12:13] offset:32
	global_load_dword v114, v110, s[12:13] offset:64
	global_load_dword v115, v110, s[12:13] offset:96
	global_load_dword v116, v110, s[12:13] offset:128
	global_load_dword v117, v110, s[12:13] offset:160
	global_load_dword v118, v110, s[12:13] offset:192
	global_load_dword v119, v110, s[12:13] offset:224
	s_cbranch_vccnz .LBB0_571
	v_or_b32_e32 v46, s14, v32
	v_ashrrev_i32_e32 v47, 31, v46
	s_ashr_i32 s15, s14, 31
	v_lshl_add_u64 v[46:47], v[46:47], 2, s[12:13]
	v_lshl_add_u64 v[48:49], s[14:15], 0, v[32:33]
	s_waitcnt vmcnt(0)
	v_mov_b32_e32 v46, v112
	v_lshl_add_u64 v[48:49], v[48:49], 2, s[12:13]
	v_mov_b32_e32 v38, v113
	s_waitcnt vmcnt(1)
	v_pk_mul_f32 v[48:49], v[0:1], v[46:47] op_sel_hi:[1,0]
	v_pk_mul_f32 v[46:47], v[2:3], v[46:47] op_sel_hi:[1,0]
	ds_write2_b32 v43, v48, v49 offset1:1
	ds_write2_b32 v43, v46, v47 offset0:2 offset1:3
	s_cbranch_execnz .LBB0_560

; #define LAS __attribute__((address_space(3)))
; __device__ __forceinline__ void tr_stage(const float* gain, int nblk, int item, int lane, const f32x4 (&wv)[8], LAS float* scr) {
;     ...
; #pragma unroll
;     for (int i = 0; i < 8; ++i) { const int kk = 8 * i + (lane >> 3); const float gk = gain ? gain[k0 + kk] : 1.0f; LAS float* d = scr + kk * 33 + 4 * (lane & 7);
;         d[0] = wv[i][0] * gk; d[1] = wv[i][1] * gk; d[2] = wv[i][2] * gk; d[3] = wv[i][3] * gk; }
.LBB0_560:
	s_waitcnt vmcnt(0)
	v_pk_mul_f32 v[46:47], v[4:5], v[38:39] op_sel_hi:[1,0]
	v_add_u32_e32 v45, 0x420, v43
	ds_write2_b32 v45, v46, v47 offset1:1
	v_pk_mul_f32 v[46:47], v[6:7], v[38:39] op_sel_hi:[1,0]
	v_add_u32_e32 v38, 0x428, v43
	ds_write2_b32 v38, v46, v47 offset1:1
	s_and_b64 vcc, exec, s[8:9]
	v_add_u32_e32 v45, 0x840, v43
	v_add_u32_e32 v46, 0x848, v43
	s_cbranch_vccnz .LBB0_572
	s_ashr_i32 s15, s14, 31
	v_lshl_add_u64 v[48:49], s[14:15], 0, v[32:33]
	v_lshl_add_u64 v[48:49], v[48:49], 2, s[12:13]
	v_mov_b32_e32 v50, v114
	v_mov_b32_e32 v38, v115
	s_waitcnt vmcnt(1)
	v_pk_mul_f32 v[48:49], v[8:9], v[50:51] op_sel_hi:[1,0]
	v_pk_mul_f32 v[50:51], v[10:11], v[50:51] op_sel_hi:[1,0]
	ds_write2_b32 v45, v48, v49 offset1:1
	ds_write2_b32 v46, v50, v51 offset1:1
	s_cbranch_execnz .LBB0_563

; #define LAS __attribute__((address_space(3)))
; __device__ __forceinline__ void tr_stage(const float* gain, int nblk, int item, int lane, const f32x4 (&wv)[8], LAS float* scr) {
;     ...
; #pragma unroll
;     for (int i = 0; i < 8; ++i) { const int kk = 8 * i + (lane >> 3); const float gk = gain ? gain[k0 + kk] : 1.0f; LAS float* d = scr + kk * 33 + 4 * (lane & 7);
;         d[0] = wv[i][0] * gk; d[1] = wv[i][1] * gk; d[2] = wv[i][2] * gk; d[3] = wv[i][3] * gk; }
.LBB0_563:
	s_waitcnt vmcnt(0)
	v_pk_mul_f32 v[46:47], v[12:13], v[38:39] op_sel_hi:[1,0]
	v_add_u32_e32 v45, 0xc60, v43
	ds_write2_b32 v45, v46, v47 offset1:1
	v_pk_mul_f32 v[46:47], v[14:15], v[38:39] op_sel_hi:[1,0]
	v_add_u32_e32 v38, 0xc68, v43
	ds_write2_b32 v38, v46, v47 offset1:1
	s_and_b64 vcc, exec, s[8:9]
	v_add_u32_e32 v45, 0x1080, v43
	v_add_u32_e32 v46, 0x1088, v43
	s_cbranch_vccnz .LBB0_573
	s_ashr_i32 s15, s14, 31
	v_lshl_add_u64 v[48:49], s[14:15], 0, v[32:33]
	v_lshl_add_u64 v[48:49], v[48:49], 2, s[12:13]
	v_mov_b32_e32 v50, v116
	v_mov_b32_e32 v38, v117
	s_waitcnt vmcnt(1)
	v_pk_mul_f32 v[48:49], v[16:17], v[50:51] op_sel_hi:[1,0]
	v_pk_mul_f32 v[50:51], v[18:19], v[50:51] op_sel_hi:[1,0]
	ds_write2_b32 v45, v48, v49 offset1:1
	ds_write2_b32 v46, v50, v51 offset1:1
	s_cbranch_execnz .LBB0_566

; #define LAS __attribute__((address_space(3)))
; __device__ __forceinline__ void tr_stage(const float* gain, int nblk, int item, int lane, const f32x4 (&wv)[8], LAS float* scr) {
;     ...
; #pragma unroll
;     for (int i = 0; i < 8; ++i) { const int kk = 8 * i + (lane >> 3); const float gk = gain ? gain[k0 + kk] : 1.0f; LAS float* d = scr + kk * 33 + 4 * (lane & 7);
;         d[0] = wv[i][0] * gk; d[1] = wv[i][1] * gk; d[2] = wv[i][2] * gk; d[3] = wv[i][3] * gk; }
.LBB0_566:
	s_waitcnt vmcnt(0)
	v_pk_mul_f32 v[46:47], v[20:21], v[38:39] op_sel_hi:[1,0]
	v_add_u32_e32 v45, 0x14a0, v43
	ds_write2_b32 v45, v46, v47 offset1:1
	v_pk_mul_f32 v[46:47], v[22:23], v[38:39] op_sel_hi:[1,0]
	v_add_u32_e32 v38, 0x14a8, v43
	ds_write2_b32 v38, v46, v47 offset1:1
	s_and_b64 vcc, exec, s[8:9]
	v_add_u32_e32 v45, 0x18c0, v43
	v_add_u32_e32 v46, 0x18c8, v43
	s_cbranch_vccnz .LBB0_574
	s_ashr_i32 s15, s14, 31
	v_lshl_add_u64 v[48:49], s[14:15], 0, v[32:33]
	v_lshl_add_u64 v[48:49], v[48:49], 2, s[12:13]
	v_mov_b32_e32 v50, v118
	v_mov_b32_e32 v38, v119
	s_waitcnt vmcnt(1)
	v_pk_mul_f32 v[48:49], v[24:25], v[50:51] op_sel_hi:[1,0]
	v_pk_mul_f32 v[50:51], v[26:27], v[50:51] op_sel_hi:[1,0]
	ds_write2_b32 v45, v48, v49 offset1:1
	ds_write2_b32 v46, v50, v51 offset1:1
	s_cbranch_execnz .LBB0_569
